# up_proj epilogue: rstd of the unit rows prefetched before the K-loop into idle registers, rstd scaling with v_pk_mul_f32
# speedup vs baseline: 1.0005x; 1.0005x over previous
.LBB0_1335:
	s_ashr_i32 s81, s80, 31
	s_lshl_b64 s[8:9], s[80:81], 20
	s_add_u32 s82, s56, s8
	s_addc_u32 s83, s57, s9
	s_and_b64 s[8:9], s[6:7], exec
	s_cselect_b32 s18, s83, s17
	s_cselect_b32 s19, s82, s16
	s_ashr_i32 s39, s38, 31
	s_lshl_b64 s[8:9], s[38:39], 20
	s_add_u32 s84, s94, s8
	s_addc_u32 s85, s95, s9
	s_and_b64 s[8:9], s[6:7], exec
	s_cselect_b32 s22, s85, s15
	s_cselect_b32 s23, s84, s14
	s_add_u32 s39, s14, 0x100
	s_addc_u32 s40, s15, 0
	s_add_u32 s8, s16, 0x80080
	v_mov_b32_e32 v4, 0
	s_addc_u32 s9, s17, 0
	s_mov_b32 s16, -2
	v_mov_b32_e32 v5, v4
	v_mov_b32_e32 v6, v4
	v_mov_b32_e32 v7, v4
	s_waitcnt vmcnt(0)
	v_and_b32_e32 v250, 15, v0
	v_mov_b32_e32 v251, s12
	v_add_u32_e32 v250, s63, v250
	v_lshl_add_u32 v250, v251, 8, v250
	v_lshlrev_b32_e32 v250, 2, v250
	global_load_dword v242, v250, s[24:25]
	global_load_dword v243, v250, s[24:25] offset:64
	global_load_dword v244, v250, s[24:25] offset:128
	global_load_dword v245, v250, s[24:25] offset:192
	global_load_dword v246, v250, s[24:25] offset:512
	global_load_dword v247, v250, s[24:25] offset:576
	global_load_dword v248, v250, s[24:25] offset:640
	global_load_dword v249, v250, s[24:25] offset:704
	v_mov_b32_e32 v68, v4
	v_mov_b32_e32 v69, v4
	v_mov_b32_e32 v70, v4
	v_mov_b32_e32 v71, v4
	v_mov_b32_e32 v12, v4
	v_mov_b32_e32 v13, v4
	v_mov_b32_e32 v14, v4
	v_mov_b32_e32 v15, v4
	v_mov_b32_e32 v76, v4
	v_mov_b32_e32 v77, v4
	v_mov_b32_e32 v78, v4
	v_mov_b32_e32 v79, v4
	v_mov_b32_e32 v20, v4
	v_mov_b32_e32 v21, v4
	v_mov_b32_e32 v22, v4
	v_mov_b32_e32 v23, v4
	v_mov_b32_e32 v84, v4
	v_mov_b32_e32 v85, v4
	v_mov_b32_e32 v86, v4
	v_mov_b32_e32 v87, v4
	v_mov_b32_e32 v60, v4
	v_mov_b32_e32 v61, v4
	v_mov_b32_e32 v62, v4
	v_mov_b32_e32 v63, v4
	v_mov_b32_e32 v124, v4
	v_mov_b32_e32 v125, v4
	v_mov_b32_e32 v126, v4
	v_mov_b32_e32 v127, v4
	v_mov_b32_e32 v8, v4
	v_mov_b32_e32 v9, v4
	v_mov_b32_e32 v10, v4
	v_mov_b32_e32 v11, v4
	v_mov_b32_e32 v72, v4
	v_mov_b32_e32 v73, v4
	v_mov_b32_e32 v74, v4
	v_mov_b32_e32 v75, v4
	v_mov_b32_e32 v16, v4
	v_mov_b32_e32 v17, v4
	v_mov_b32_e32 v18, v4
	v_mov_b32_e32 v19, v4
	v_mov_b32_e32 v80, v4
	v_mov_b32_e32 v81, v4
	v_mov_b32_e32 v82, v4
	v_mov_b32_e32 v83, v4
	v_mov_b32_e32 v24, v4
	v_mov_b32_e32 v25, v4
	v_mov_b32_e32 v26, v4
	v_mov_b32_e32 v27, v4
	v_mov_b32_e32 v88, v4
	v_mov_b32_e32 v89, v4
	v_mov_b32_e32 v90, v4
	v_mov_b32_e32 v91, v4
	v_mov_b32_e32 v64, v4
	v_mov_b32_e32 v65, v4
	v_mov_b32_e32 v66, v4
	v_mov_b32_e32 v67, v4
	v_mov_b32_e32 v128, v4
	v_mov_b32_e32 v129, v4
	v_mov_b32_e32 v130, v4
	v_mov_b32_e32 v131, v4
	v_mov_b32_e32 v132, v4
	v_mov_b32_e32 v133, v4
	v_mov_b32_e32 v134, v4
	v_mov_b32_e32 v135, v4
	v_mov_b32_e32 v164, v4
	v_mov_b32_e32 v165, v4
	v_mov_b32_e32 v166, v4
	v_mov_b32_e32 v167, v4
	v_mov_b32_e32 v140, v4
	v_mov_b32_e32 v141, v4
	v_mov_b32_e32 v142, v4
	v_mov_b32_e32 v143, v4
	v_mov_b32_e32 v172, v4
	v_mov_b32_e32 v173, v4
	v_mov_b32_e32 v174, v4
	v_mov_b32_e32 v175, v4
	v_mov_b32_e32 v148, v4
	v_mov_b32_e32 v149, v4
	v_mov_b32_e32 v150, v4
	v_mov_b32_e32 v151, v4
	v_mov_b32_e32 v184, v4
	v_mov_b32_e32 v185, v4
	v_mov_b32_e32 v186, v4
	v_mov_b32_e32 v187, v4
	v_mov_b32_e32 v156, v4
	v_mov_b32_e32 v157, v4
	v_mov_b32_e32 v158, v4
	v_mov_b32_e32 v159, v4
	v_mov_b32_e32 v180, v4
	v_mov_b32_e32 v181, v4
	v_mov_b32_e32 v182, v4
	v_mov_b32_e32 v183, v4
	v_mov_b32_e32 v136, v4
	v_mov_b32_e32 v137, v4
	v_mov_b32_e32 v138, v4
	v_mov_b32_e32 v139, v4
	v_mov_b32_e32 v168, v4
	v_mov_b32_e32 v169, v4
	v_mov_b32_e32 v170, v4
	v_mov_b32_e32 v171, v4
	v_mov_b32_e32 v144, v4
	v_mov_b32_e32 v145, v4
	v_mov_b32_e32 v146, v4
	v_mov_b32_e32 v147, v4
	v_mov_b32_e32 v176, v4
	v_mov_b32_e32 v177, v4
	v_mov_b32_e32 v178, v4
	v_mov_b32_e32 v179, v4
	v_mov_b32_e32 v152, v4
	v_mov_b32_e32 v153, v4
	v_mov_b32_e32 v154, v4
	v_mov_b32_e32 v155, v4
	v_mov_b32_e32 v188, v4
	v_mov_b32_e32 v189, v4
	v_mov_b32_e32 v190, v4
	v_mov_b32_e32 v191, v4
	v_mov_b32_e32 v160, v4
	v_mov_b32_e32 v161, v4
	v_mov_b32_e32 v162, v4
	v_mov_b32_e32 v163, v4
	v_mov_b32_e32 v192, v4
	v_mov_b32_e32 v193, v4
	v_mov_b32_e32 v194, v4
	v_mov_b32_e32 v195, v4
	s_mov_b64 s[20:21], 0x80

.LBB0_1339:
	v_and_b32_e32 v56, 15, v0
	v_bfe_u32 v57, v0, 4, 2
	s_lshl_b32 s8, s12, 8
	s_add_i32 s8, s8, s63
	s_lshl_b32 s9, s13, 9
	s_lshl_b32 s22, s64, 2
	s_add_i32 s9, s9, s22
	v_lshl_add_u32 v235, v57, 5, s9
	global_load_dwordx4 v[100:103], v235, s[0:1]
	global_load_dwordx4 v[104:107], v235, s[30:31]
	global_load_dwordx4 v[112:115], v235, s[34:35]
	global_load_dwordx4 v[120:123], v235, s[2:3]
	global_load_dwordx4 v[92:95], v235, s[36:37]
	global_load_dwordx4 v[96:99], v235, s[48:49]
	global_load_dwordx4 v[108:111], v235, s[46:47]
	global_load_dwordx4 v[116:119], v235, s[44:45]
	v_cmp_lt_u32_e64 s[10:11], 13, v56
	v_cmp_gt_u32_e64 s[14:15], 2, v56
	v_cmp_eq_u32_e64 s[22:23], 0, v56
	v_lshlrev_b32_e32 v217, 8, v56
	v_lshl_add_u32 v217, v57, 5, v217
	v_add_u32_e32 v217, 0xfffff200, v217
	v_cndmask_b32_e64 v250, 0, 1.0, s[22:23]
	v_cndmask_b32_e64 v251, 0, 1.0, s[14:15]
	v_mul_u32_u24_e32 v234, 0x2c00, v56
	v_lshl_add_u32 v234, v57, 4, v234
	s_mov_b32 s41, 0xbfb8aa3b
	s_lshl_b32 s39, s12, 8
	s_add_i32 s39, s39, s63
	s_mul_i32 s39, s39, 0x2c00
	s_lshl_b32 s40, s13, 8
	s_add_i32 s39, s39, s40
	s_lshl_b32 s40, s64, 1
	s_add_i32 s39, s39, s40
	s_add_u32 s16, s70, s39
	s_addc_u32 s17, s71, 0
	s_add_u32 s18, s16, 0x160000
	s_addc_u32 s19, s17, 0
	v_pk_mul_f32 v[192:193], v[192:193], v[242:243] op_sel_hi:[1,0]
	v_pk_mul_f32 v[194:195], v[194:195], v[242:243] op_sel_hi:[1,0]
	v_pk_mul_f32 v[160:161], v[160:161], v[242:243] op_sel_hi:[1,0]
	v_pk_mul_f32 v[162:163], v[162:163], v[242:243] op_sel_hi:[1,0]
	v_pk_mul_f32 v[180:181], v[180:181], v[242:243] op_sel_hi:[1,0]
	v_pk_mul_f32 v[182:183], v[182:183], v[242:243] op_sel_hi:[1,0]
	v_pk_mul_f32 v[156:157], v[156:157], v[242:243] op_sel_hi:[1,0]
	v_pk_mul_f32 v[158:159], v[158:159], v[242:243] op_sel_hi:[1,0]
	v_pk_mul_f32 v[188:189], v[188:189], v[242:243] op_sel:[0,1] op_sel_hi:[1,1]
	v_pk_mul_f32 v[190:191], v[190:191], v[242:243] op_sel:[0,1] op_sel_hi:[1,1]
	v_pk_mul_f32 v[152:153], v[152:153], v[242:243] op_sel:[0,1] op_sel_hi:[1,1]
	v_pk_mul_f32 v[154:155], v[154:155], v[242:243] op_sel:[0,1] op_sel_hi:[1,1]
	v_pk_mul_f32 v[184:185], v[184:185], v[242:243] op_sel:[0,1] op_sel_hi:[1,1]
	v_pk_mul_f32 v[186:187], v[186:187], v[242:243] op_sel:[0,1] op_sel_hi:[1,1]
	v_pk_mul_f32 v[148:149], v[148:149], v[242:243] op_sel:[0,1] op_sel_hi:[1,1]
	v_pk_mul_f32 v[150:151], v[150:151], v[242:243] op_sel:[0,1] op_sel_hi:[1,1]
	v_pk_mul_f32 v[176:177], v[176:177], v[244:245] op_sel_hi:[1,0]
	v_pk_mul_f32 v[178:179], v[178:179], v[244:245] op_sel_hi:[1,0]
	v_pk_mul_f32 v[144:145], v[144:145], v[244:245] op_sel_hi:[1,0]
	v_pk_mul_f32 v[146:147], v[146:147], v[244:245] op_sel_hi:[1,0]
	v_pk_mul_f32 v[172:173], v[172:173], v[244:245] op_sel_hi:[1,0]
	v_pk_mul_f32 v[174:175], v[174:175], v[244:245] op_sel_hi:[1,0]
	v_pk_mul_f32 v[140:141], v[140:141], v[244:245] op_sel_hi:[1,0]
	v_pk_mul_f32 v[142:143], v[142:143], v[244:245] op_sel_hi:[1,0]
	v_pk_mul_f32 v[168:169], v[168:169], v[244:245] op_sel:[0,1] op_sel_hi:[1,1]
	v_pk_mul_f32 v[170:171], v[170:171], v[244:245] op_sel:[0,1] op_sel_hi:[1,1]
	v_pk_mul_f32 v[136:137], v[136:137], v[244:245] op_sel:[0,1] op_sel_hi:[1,1]
	v_pk_mul_f32 v[138:139], v[138:139], v[244:245] op_sel:[0,1] op_sel_hi:[1,1]
	v_pk_mul_f32 v[164:165], v[164:165], v[244:245] op_sel:[0,1] op_sel_hi:[1,1]
	v_pk_mul_f32 v[166:167], v[166:167], v[244:245] op_sel:[0,1] op_sel_hi:[1,1]
	v_pk_mul_f32 v[132:133], v[132:133], v[244:245] op_sel:[0,1] op_sel_hi:[1,1]
	v_pk_mul_f32 v[134:135], v[134:135], v[244:245] op_sel:[0,1] op_sel_hi:[1,1]
	v_pk_mul_f32 v[128:129], v[128:129], v[246:247] op_sel_hi:[1,0]
	v_pk_mul_f32 v[130:131], v[130:131], v[246:247] op_sel_hi:[1,0]
	v_pk_mul_f32 v[64:65], v[64:65], v[246:247] op_sel_hi:[1,0]
	v_pk_mul_f32 v[66:67], v[66:67], v[246:247] op_sel_hi:[1,0]
	v_pk_mul_f32 v[124:125], v[124:125], v[246:247] op_sel_hi:[1,0]
	v_pk_mul_f32 v[126:127], v[126:127], v[246:247] op_sel_hi:[1,0]
	v_pk_mul_f32 v[60:61], v[60:61], v[246:247] op_sel_hi:[1,0]
	v_pk_mul_f32 v[62:63], v[62:63], v[246:247] op_sel_hi:[1,0]
	v_pk_mul_f32 v[88:89], v[88:89], v[246:247] op_sel:[0,1] op_sel_hi:[1,1]
	v_pk_mul_f32 v[90:91], v[90:91], v[246:247] op_sel:[0,1] op_sel_hi:[1,1]
	v_pk_mul_f32 v[24:25], v[24:25], v[246:247] op_sel:[0,1] op_sel_hi:[1,1]
	v_pk_mul_f32 v[26:27], v[26:27], v[246:247] op_sel:[0,1] op_sel_hi:[1,1]
	v_pk_mul_f32 v[84:85], v[84:85], v[246:247] op_sel:[0,1] op_sel_hi:[1,1]
	v_pk_mul_f32 v[86:87], v[86:87], v[246:247] op_sel:[0,1] op_sel_hi:[1,1]
	v_pk_mul_f32 v[20:21], v[20:21], v[246:247] op_sel:[0,1] op_sel_hi:[1,1]
	v_pk_mul_f32 v[22:23], v[22:23], v[246:247] op_sel:[0,1] op_sel_hi:[1,1]
	v_pk_mul_f32 v[80:81], v[80:81], v[248:249] op_sel_hi:[1,0]
	v_pk_mul_f32 v[82:83], v[82:83], v[248:249] op_sel_hi:[1,0]
	v_pk_mul_f32 v[16:17], v[16:17], v[248:249] op_sel_hi:[1,0]
	v_pk_mul_f32 v[18:19], v[18:19], v[248:249] op_sel_hi:[1,0]
	v_pk_mul_f32 v[76:77], v[76:77], v[248:249] op_sel_hi:[1,0]
	v_pk_mul_f32 v[78:79], v[78:79], v[248:249] op_sel_hi:[1,0]
	v_pk_mul_f32 v[12:13], v[12:13], v[248:249] op_sel_hi:[1,0]
	v_pk_mul_f32 v[14:15], v[14:15], v[248:249] op_sel_hi:[1,0]
	v_pk_mul_f32 v[72:73], v[72:73], v[248:249] op_sel:[0,1] op_sel_hi:[1,1]
	v_pk_mul_f32 v[74:75], v[74:75], v[248:249] op_sel:[0,1] op_sel_hi:[1,1]
	v_pk_mul_f32 v[8:9], v[8:9], v[248:249] op_sel:[0,1] op_sel_hi:[1,1]
	v_pk_mul_f32 v[10:11], v[10:11], v[248:249] op_sel:[0,1] op_sel_hi:[1,1]
	v_pk_mul_f32 v[68:69], v[68:69], v[248:249] op_sel:[0,1] op_sel_hi:[1,1]
	v_pk_mul_f32 v[70:71], v[70:71], v[248:249] op_sel:[0,1] op_sel_hi:[1,1]
	v_pk_mul_f32 v[4:5], v[4:5], v[248:249] op_sel:[0,1] op_sel_hi:[1,1]
	v_pk_mul_f32 v[6:7], v[6:7], v[248:249] op_sel:[0,1] op_sel_hi:[1,1]
	v_add_u32_e32 v58, s78, v217
	s_and_saveexec_b64 s[8:9], s[10:11]
	ds_write_b128 v58, v[168:171]
	ds_write_b128 v58, v[136:139] offset:16
	ds_write_b128 v58, v[164:167] offset:128
	ds_write_b128 v58, v[132:135] offset:144
	ds_write_b128 v58, v[72:75] offset:4096
	ds_write_b128 v58, v[8:11] offset:4112
	ds_write_b128 v58, v[68:71] offset:4224
	ds_write_b128 v58, v[4:7] offset:4240
	s_mov_b64 exec, s[8:9]
	s_waitcnt lgkmcnt(0)
	s_barrier
	s_waitcnt vmcnt(0)
	v_mul_f32_e32 v28, v104, v250
	v_mul_f32_e32 v29, v105, v250
	v_mul_f32_e32 v30, v106, v250
	v_mul_f32_e32 v31, v107, v250
	v_mul_f32_e32 v32, v100, v251
	v_mul_f32_e32 v33, v101, v251
	v_mul_f32_e32 v34, v102, v251
	v_mul_f32_e32 v35, v103, v251
	v_mul_f32_e32 v36, v96, v250
	v_mul_f32_e32 v37, v97, v250
	v_mul_f32_e32 v38, v98, v250
	v_mul_f32_e32 v39, v99, v250
	v_mul_f32_e32 v40, v92, v251
	v_mul_f32_e32 v41, v93, v251
	v_mul_f32_e32 v42, v94, v251
	v_mul_f32_e32 v43, v95, v251
	v_mov_b32_e32 v196, 0
	v_mov_b32_e32 v197, 0
	v_mov_b32_e32 v198, 0
	v_mov_b32_e32 v199, 0
	v_mov_b32_e32 v200, 0
	v_mov_b32_e32 v201, 0
	v_mov_b32_e32 v202, 0
	v_mov_b32_e32 v203, 0
	v_mov_b32_e32 v204, 0
	v_mov_b32_e32 v205, 0
	v_mov_b32_e32 v206, 0
	v_mov_b32_e32 v207, 0
	v_mov_b32_e32 v208, 0
	v_mov_b32_e32 v209, 0
	v_mov_b32_e32 v210, 0
	v_mov_b32_e32 v211, 0
	s_cmp_eq_u32 s63, 0
	s_cbranch_scc1 .Leu_pv0_skip_n0
	v_add_u32_e32 v58, s67, v217
	s_and_saveexec_b64 s[8:9], s[10:11]
	ds_read_b128 v[196:199], v58 offset:0
	ds_read_b128 v[200:203], v58 offset:128
	s_mov_b64 exec, s[8:9]
